# P5 epilogue: the f32 residual x loads (last read of x) marked nt so they do not allocate in the caches
# baseline (speedup 1.0000x reference)
.LBB0_1082:
	v_lshl_add_u32 v164, s47, 8, v148
	v_and_b32_e32 v155, 12, v150
	v_add_u32_e32 v155, v150, v155
	v_lshl_or_b32 v144, s22, 8, v155
	v_ashrrev_i32_e32 v165, 31, v164
	v_ashrrev_i32_e32 v145, 31, v144
	v_lshlrev_b64 v[156:157], 11, v[164:165]
	v_lshl_add_u64 v[156:157], v[156:157], 0, v[144:145]
	v_lshl_add_u64 v[160:161], v[156:157], 2, s[48:49]
	v_lshl_add_u64 v[162:163], v[156:157], 1, s[8:9]
	global_load_dwordx4 v[168:171], v[160:161], off nt
	global_load_dwordx4 v[172:175], v[160:161], off offset:16 nt
	global_load_dwordx4 v[176:179], v[160:161], off offset:512 nt
	global_load_dwordx4 v[180:183], v[160:161], off offset:528 nt
	v_mov_b64_e32 v[216:217], v[160:161]
	v_mov_b64_e32 v[218:219], v[162:163]
	v_xor_b32_e32 v194, 16, v154
	v_lshlrev_b32_e32 v194, 2, v194
	v_xor_b32_e32 v195, 32, v154
	v_lshlrev_b32_e32 v195, 2, v195
	s_mov_b32 s90, 0x10000
	s_mov_b32 s91, 0
	s_mov_b32 s92, 0x80000
	s_mov_b32 s93, 0
	s_mov_b32 s94, 0x20000
	s_mov_b32 s95, 0
	s_mov_b32 s96, 0x100000
	s_mov_b32 s97, 0
	v_lshl_add_u64 v[160:161], v[160:161], 0, s[94:95]
	global_load_dwordx4 v[200:203], v[160:161], off nt
	global_load_dwordx4 v[204:207], v[160:161], off offset:16 nt
	global_load_dwordx4 v[208:211], v[160:161], off offset:512 nt
	global_load_dwordx4 v[212:215], v[160:161], off offset:528 nt
	s_waitcnt vmcnt(4)
	v_pk_add_f32 v[124:125], v[124:125], v[168:169]
	v_pk_add_f32 v[126:127], v[126:127], v[170:171]
	v_cvt_pk_bf16_f32 v184, v124, v125
	v_cvt_pk_bf16_f32 v185, v126, v127
	v_mul_f32_e32 v192, v124, v124
	v_fmac_f32_e32 v192, v125, v125
	v_fmac_f32_e32 v192, v126, v126
	v_fmac_f32_e32 v192, v127, v127
	v_pk_add_f32 v[120:121], v[120:121], v[172:173]
	v_pk_add_f32 v[122:123], v[122:123], v[174:175]
	v_cvt_pk_bf16_f32 v186, v120, v121
	v_cvt_pk_bf16_f32 v187, v122, v123
	v_fmac_f32_e32 v192, v120, v120
	v_fmac_f32_e32 v192, v121, v121
	v_fmac_f32_e32 v192, v122, v122
	v_fmac_f32_e32 v192, v123, v123
	global_store_dwordx4 v[162:163], v[184:187], off
	v_pk_add_f32 v[116:117], v[116:117], v[176:177]
	v_pk_add_f32 v[118:119], v[118:119], v[178:179]
	v_cvt_pk_bf16_f32 v188, v116, v117
	v_cvt_pk_bf16_f32 v189, v118, v119
	v_fmac_f32_e32 v192, v116, v116
	v_fmac_f32_e32 v192, v117, v117
	v_fmac_f32_e32 v192, v118, v118
	v_fmac_f32_e32 v192, v119, v119
	v_pk_add_f32 v[112:113], v[112:113], v[180:181]
	v_pk_add_f32 v[114:115], v[114:115], v[182:183]
	v_cvt_pk_bf16_f32 v190, v112, v113
	v_cvt_pk_bf16_f32 v191, v114, v115
	v_fmac_f32_e32 v192, v112, v112
	v_fmac_f32_e32 v192, v113, v113
	v_fmac_f32_e32 v192, v114, v114
	v_fmac_f32_e32 v192, v115, v115
	global_store_dwordx4 v[162:163], v[188:191], off offset:256
	ds_bpermute_b32 v193, v194, v192
	s_waitcnt lgkmcnt(0)
	v_add_f32_e32 v192, v192, v193
	ds_bpermute_b32 v193, v195, v192
	v_lshl_add_u64 v[196:197], v[164:165], 2, s[10:11]
	s_waitcnt lgkmcnt(0)
	v_add_f32_e32 v192, v192, v193
	s_and_saveexec_b64 s[22:23], s[0:1]
	global_atomic_add_f32 v[196:197], v192, off
	s_or_b64 exec, exec, s[22:23]
	v_lshl_add_u64 v[162:163], v[162:163], 0, s[90:91]
	v_add_u32_e32 v164, 16, v164
	v_lshl_add_u64 v[160:161], v[160:161], 0, s[94:95]
	global_load_dwordx4 v[168:171], v[160:161], off nt
	global_load_dwordx4 v[172:175], v[160:161], off offset:16 nt
	global_load_dwordx4 v[176:179], v[160:161], off offset:512 nt
	global_load_dwordx4 v[180:183], v[160:161], off offset:528 nt
	s_waitcnt vmcnt(6)
	v_pk_add_f32 v[108:109], v[108:109], v[200:201]
	v_pk_add_f32 v[110:111], v[110:111], v[202:203]
	v_cvt_pk_bf16_f32 v184, v108, v109
	v_cvt_pk_bf16_f32 v185, v110, v111
	v_mul_f32_e32 v192, v108, v108
	v_fmac_f32_e32 v192, v109, v109
	v_fmac_f32_e32 v192, v110, v110
	v_fmac_f32_e32 v192, v111, v111
	v_pk_add_f32 v[104:105], v[104:105], v[204:205]
	v_pk_add_f32 v[106:107], v[106:107], v[206:207]
	v_cvt_pk_bf16_f32 v186, v104, v105
	v_cvt_pk_bf16_f32 v187, v106, v107
	v_fmac_f32_e32 v192, v104, v104
	v_fmac_f32_e32 v192, v105, v105
	v_fmac_f32_e32 v192, v106, v106
	v_fmac_f32_e32 v192, v107, v107
	global_store_dwordx4 v[162:163], v[184:187], off
	v_pk_add_f32 v[100:101], v[100:101], v[208:209]
	v_pk_add_f32 v[102:103], v[102:103], v[210:211]
	v_cvt_pk_bf16_f32 v188, v100, v101
	v_cvt_pk_bf16_f32 v189, v102, v103
	v_fmac_f32_e32 v192, v100, v100
	v_fmac_f32_e32 v192, v101, v101
	v_fmac_f32_e32 v192, v102, v102
	v_fmac_f32_e32 v192, v103, v103
	v_pk_add_f32 v[96:97], v[96:97], v[212:213]
	v_pk_add_f32 v[98:99], v[98:99], v[214:215]
	v_cvt_pk_bf16_f32 v190, v96, v97
	v_cvt_pk_bf16_f32 v191, v98, v99
	v_fmac_f32_e32 v192, v96, v96
	v_fmac_f32_e32 v192, v97, v97
	v_fmac_f32_e32 v192, v98, v98
	v_fmac_f32_e32 v192, v99, v99
	global_store_dwordx4 v[162:163], v[188:191], off offset:256
	ds_bpermute_b32 v193, v194, v192
	s_waitcnt lgkmcnt(0)
	v_add_f32_e32 v192, v192, v193
	ds_bpermute_b32 v193, v195, v192
	v_lshl_add_u64 v[196:197], v[164:165], 2, s[10:11]
	s_waitcnt lgkmcnt(0)
	v_add_f32_e32 v192, v192, v193
	s_and_saveexec_b64 s[22:23], s[0:1]
	global_atomic_add_f32 v[196:197], v192, off
	s_or_b64 exec, exec, s[22:23]
	v_lshl_add_u64 v[162:163], v[162:163], 0, s[90:91]
	v_add_u32_e32 v164, 16, v164
	v_lshl_add_u64 v[160:161], v[160:161], 0, s[94:95]
	global_load_dwordx4 v[200:203], v[160:161], off nt
	global_load_dwordx4 v[204:207], v[160:161], off offset:16 nt
	global_load_dwordx4 v[208:211], v[160:161], off offset:512 nt
	global_load_dwordx4 v[212:215], v[160:161], off offset:528 nt
	s_waitcnt vmcnt(6)
	v_pk_add_f32 v[92:93], v[92:93], v[168:169]
	v_pk_add_f32 v[94:95], v[94:95], v[170:171]
	v_cvt_pk_bf16_f32 v184, v92, v93
	v_cvt_pk_bf16_f32 v185, v94, v95
	v_mul_f32_e32 v192, v92, v92
	v_fmac_f32_e32 v192, v93, v93
	v_fmac_f32_e32 v192, v94, v94
	v_fmac_f32_e32 v192, v95, v95
	v_pk_add_f32 v[88:89], v[88:89], v[172:173]
	v_pk_add_f32 v[90:91], v[90:91], v[174:175]
	v_cvt_pk_bf16_f32 v186, v88, v89
	v_cvt_pk_bf16_f32 v187, v90, v91
	v_fmac_f32_e32 v192, v88, v88
	v_fmac_f32_e32 v192, v89, v89
	v_fmac_f32_e32 v192, v90, v90
	v_fmac_f32_e32 v192, v91, v91
	global_store_dwordx4 v[162:163], v[184:187], off
	v_pk_add_f32 v[84:85], v[84:85], v[176:177]
	v_pk_add_f32 v[86:87], v[86:87], v[178:179]
	v_cvt_pk_bf16_f32 v188, v84, v85
	v_cvt_pk_bf16_f32 v189, v86, v87
	v_fmac_f32_e32 v192, v84, v84
	v_fmac_f32_e32 v192, v85, v85
	v_fmac_f32_e32 v192, v86, v86
	v_fmac_f32_e32 v192, v87, v87
	v_pk_add_f32 v[80:81], v[80:81], v[180:181]
	v_pk_add_f32 v[82:83], v[82:83], v[182:183]
	v_cvt_pk_bf16_f32 v190, v80, v81
	v_cvt_pk_bf16_f32 v191, v82, v83
	v_fmac_f32_e32 v192, v80, v80
	v_fmac_f32_e32 v192, v81, v81
	v_fmac_f32_e32 v192, v82, v82
	v_fmac_f32_e32 v192, v83, v83
	global_store_dwordx4 v[162:163], v[188:191], off offset:256
	ds_bpermute_b32 v193, v194, v192
	s_waitcnt lgkmcnt(0)
	v_add_f32_e32 v192, v192, v193
	ds_bpermute_b32 v193, v195, v192
	v_lshl_add_u64 v[196:197], v[164:165], 2, s[10:11]
	s_waitcnt lgkmcnt(0)
	v_add_f32_e32 v192, v192, v193
	s_and_saveexec_b64 s[22:23], s[0:1]
	global_atomic_add_f32 v[196:197], v192, off
	s_or_b64 exec, exec, s[22:23]
	v_lshl_add_u64 v[162:163], v[162:163], 0, s[90:91]
	v_add_u32_e32 v164, 16, v164
	v_lshl_add_u64 v[160:161], v[216:217], 0, s[96:97]
	global_load_dwordx4 v[168:171], v[160:161], off nt
	global_load_dwordx4 v[172:175], v[160:161], off offset:16 nt
	global_load_dwordx4 v[176:179], v[160:161], off offset:512 nt
	global_load_dwordx4 v[180:183], v[160:161], off offset:528 nt
	s_waitcnt vmcnt(6)
	v_pk_add_f32 v[76:77], v[76:77], v[200:201]
	v_pk_add_f32 v[78:79], v[78:79], v[202:203]
	v_cvt_pk_bf16_f32 v184, v76, v77
	v_cvt_pk_bf16_f32 v185, v78, v79
	v_mul_f32_e32 v192, v76, v76
	v_fmac_f32_e32 v192, v77, v77
	v_fmac_f32_e32 v192, v78, v78
	v_fmac_f32_e32 v192, v79, v79
	v_pk_add_f32 v[72:73], v[72:73], v[204:205]
	v_pk_add_f32 v[74:75], v[74:75], v[206:207]
	v_cvt_pk_bf16_f32 v186, v72, v73
	v_cvt_pk_bf16_f32 v187, v74, v75
	v_fmac_f32_e32 v192, v72, v72
	v_fmac_f32_e32 v192, v73, v73
	v_fmac_f32_e32 v192, v74, v74
	v_fmac_f32_e32 v192, v75, v75
	global_store_dwordx4 v[162:163], v[184:187], off
	v_pk_add_f32 v[68:69], v[68:69], v[208:209]
	v_pk_add_f32 v[70:71], v[70:71], v[210:211]
	v_cvt_pk_bf16_f32 v188, v68, v69
	v_cvt_pk_bf16_f32 v189, v70, v71
	v_fmac_f32_e32 v192, v68, v68
	v_fmac_f32_e32 v192, v69, v69
	v_fmac_f32_e32 v192, v70, v70
	v_fmac_f32_e32 v192, v71, v71
	v_pk_add_f32 v[64:65], v[64:65], v[212:213]
	v_pk_add_f32 v[66:67], v[66:67], v[214:215]
	v_cvt_pk_bf16_f32 v190, v64, v65
	v_cvt_pk_bf16_f32 v191, v66, v67
	v_fmac_f32_e32 v192, v64, v64
	v_fmac_f32_e32 v192, v65, v65
	v_fmac_f32_e32 v192, v66, v66
	v_fmac_f32_e32 v192, v67, v67
	global_store_dwordx4 v[162:163], v[188:191], off offset:256
	ds_bpermute_b32 v193, v194, v192
	s_waitcnt lgkmcnt(0)
	v_add_f32_e32 v192, v192, v193
	ds_bpermute_b32 v193, v195, v192
	v_lshl_add_u64 v[196:197], v[164:165], 2, s[10:11]
	s_waitcnt lgkmcnt(0)
	v_add_f32_e32 v192, v192, v193
	s_and_saveexec_b64 s[22:23], s[0:1]
	global_atomic_add_f32 v[196:197], v192, off
	s_or_b64 exec, exec, s[22:23]
	v_lshl_add_u64 v[162:163], v[218:219], 0, s[92:93]
	v_add_u32_e32 v164, 0x50, v164
	v_lshl_add_u64 v[160:161], v[160:161], 0, s[94:95]
	global_load_dwordx4 v[200:203], v[160:161], off nt
	global_load_dwordx4 v[204:207], v[160:161], off offset:16 nt
	global_load_dwordx4 v[208:211], v[160:161], off offset:512 nt
	global_load_dwordx4 v[212:215], v[160:161], off offset:528 nt
	s_waitcnt vmcnt(6)
	v_pk_add_f32 v[60:61], v[60:61], v[168:169]
	v_pk_add_f32 v[62:63], v[62:63], v[170:171]
	v_cvt_pk_bf16_f32 v184, v60, v61
	v_cvt_pk_bf16_f32 v185, v62, v63
	v_mul_f32_e32 v192, v60, v60
	v_fmac_f32_e32 v192, v61, v61
	v_fmac_f32_e32 v192, v62, v62
	v_fmac_f32_e32 v192, v63, v63
	v_pk_add_f32 v[56:57], v[56:57], v[172:173]
	v_pk_add_f32 v[58:59], v[58:59], v[174:175]
	v_cvt_pk_bf16_f32 v186, v56, v57
	v_cvt_pk_bf16_f32 v187, v58, v59
	v_fmac_f32_e32 v192, v56, v56
	v_fmac_f32_e32 v192, v57, v57
	v_fmac_f32_e32 v192, v58, v58
	v_fmac_f32_e32 v192, v59, v59
	global_store_dwordx4 v[162:163], v[184:187], off
	v_pk_add_f32 v[52:53], v[52:53], v[176:177]
	v_pk_add_f32 v[54:55], v[54:55], v[178:179]
	v_cvt_pk_bf16_f32 v188, v52, v53
	v_cvt_pk_bf16_f32 v189, v54, v55
	v_fmac_f32_e32 v192, v52, v52
	v_fmac_f32_e32 v192, v53, v53
	v_fmac_f32_e32 v192, v54, v54
	v_fmac_f32_e32 v192, v55, v55
	v_pk_add_f32 v[48:49], v[48:49], v[180:181]
	v_pk_add_f32 v[50:51], v[50:51], v[182:183]
	v_cvt_pk_bf16_f32 v190, v48, v49
	v_cvt_pk_bf16_f32 v191, v50, v51
	v_fmac_f32_e32 v192, v48, v48
	v_fmac_f32_e32 v192, v49, v49
	v_fmac_f32_e32 v192, v50, v50
	v_fmac_f32_e32 v192, v51, v51
	global_store_dwordx4 v[162:163], v[188:191], off offset:256
	ds_bpermute_b32 v193, v194, v192
	s_waitcnt lgkmcnt(0)
	v_add_f32_e32 v192, v192, v193
	ds_bpermute_b32 v193, v195, v192
	v_lshl_add_u64 v[196:197], v[164:165], 2, s[10:11]
	s_waitcnt lgkmcnt(0)
	v_add_f32_e32 v192, v192, v193
	s_and_saveexec_b64 s[22:23], s[0:1]
	global_atomic_add_f32 v[196:197], v192, off
	s_or_b64 exec, exec, s[22:23]
	v_lshl_add_u64 v[162:163], v[162:163], 0, s[90:91]
	v_add_u32_e32 v164, 16, v164
	v_lshl_add_u64 v[160:161], v[160:161], 0, s[94:95]
	global_load_dwordx4 v[168:171], v[160:161], off nt
	global_load_dwordx4 v[172:175], v[160:161], off offset:16 nt
	global_load_dwordx4 v[176:179], v[160:161], off offset:512 nt
	global_load_dwordx4 v[180:183], v[160:161], off offset:528 nt
	s_waitcnt vmcnt(6)
	v_pk_add_f32 v[44:45], v[44:45], v[200:201]
	v_pk_add_f32 v[46:47], v[46:47], v[202:203]
	v_cvt_pk_bf16_f32 v184, v44, v45
	v_cvt_pk_bf16_f32 v185, v46, v47
	v_mul_f32_e32 v192, v44, v44
	v_fmac_f32_e32 v192, v45, v45
	v_fmac_f32_e32 v192, v46, v46
	v_fmac_f32_e32 v192, v47, v47
	v_pk_add_f32 v[40:41], v[40:41], v[204:205]
	v_pk_add_f32 v[42:43], v[42:43], v[206:207]
	v_cvt_pk_bf16_f32 v186, v40, v41
	v_cvt_pk_bf16_f32 v187, v42, v43
	v_fmac_f32_e32 v192, v40, v40
	v_fmac_f32_e32 v192, v41, v41
	v_fmac_f32_e32 v192, v42, v42
	v_fmac_f32_e32 v192, v43, v43
	global_store_dwordx4 v[162:163], v[184:187], off
	v_pk_add_f32 v[36:37], v[36:37], v[208:209]
	v_pk_add_f32 v[38:39], v[38:39], v[210:211]
	v_cvt_pk_bf16_f32 v188, v36, v37
	v_cvt_pk_bf16_f32 v189, v38, v39
	v_fmac_f32_e32 v192, v36, v36
	v_fmac_f32_e32 v192, v37, v37
	v_fmac_f32_e32 v192, v38, v38
	v_fmac_f32_e32 v192, v39, v39
	v_pk_add_f32 v[32:33], v[32:33], v[212:213]
	v_pk_add_f32 v[34:35], v[34:35], v[214:215]
	v_cvt_pk_bf16_f32 v190, v32, v33
	v_cvt_pk_bf16_f32 v191, v34, v35
	v_fmac_f32_e32 v192, v32, v32
	v_fmac_f32_e32 v192, v33, v33
	v_fmac_f32_e32 v192, v34, v34
	v_fmac_f32_e32 v192, v35, v35
	global_store_dwordx4 v[162:163], v[188:191], off offset:256
	ds_bpermute_b32 v193, v194, v192
	s_waitcnt lgkmcnt(0)
	v_add_f32_e32 v192, v192, v193
	ds_bpermute_b32 v193, v195, v192
	v_lshl_add_u64 v[196:197], v[164:165], 2, s[10:11]
	s_waitcnt lgkmcnt(0)
	v_add_f32_e32 v192, v192, v193
	s_and_saveexec_b64 s[22:23], s[0:1]
	global_atomic_add_f32 v[196:197], v192, off
	s_or_b64 exec, exec, s[22:23]
	v_lshl_add_u64 v[162:163], v[162:163], 0, s[90:91]
	v_add_u32_e32 v164, 16, v164
	v_lshl_add_u64 v[160:161], v[160:161], 0, s[94:95]
	global_load_dwordx4 v[200:203], v[160:161], off nt
	global_load_dwordx4 v[204:207], v[160:161], off offset:16 nt
	global_load_dwordx4 v[208:211], v[160:161], off offset:512 nt
	global_load_dwordx4 v[212:215], v[160:161], off offset:528 nt
	s_waitcnt vmcnt(6)
	v_pk_add_f32 v[28:29], v[28:29], v[168:169]
	v_pk_add_f32 v[30:31], v[30:31], v[170:171]
	v_cvt_pk_bf16_f32 v184, v28, v29
	v_cvt_pk_bf16_f32 v185, v30, v31
	v_mul_f32_e32 v192, v28, v28
	v_fmac_f32_e32 v192, v29, v29
	v_fmac_f32_e32 v192, v30, v30
	v_fmac_f32_e32 v192, v31, v31
	v_pk_add_f32 v[24:25], v[24:25], v[172:173]
	v_pk_add_f32 v[26:27], v[26:27], v[174:175]
	v_cvt_pk_bf16_f32 v186, v24, v25
	v_cvt_pk_bf16_f32 v187, v26, v27
	v_fmac_f32_e32 v192, v24, v24
	v_fmac_f32_e32 v192, v25, v25
	v_fmac_f32_e32 v192, v26, v26
	v_fmac_f32_e32 v192, v27, v27
	global_store_dwordx4 v[162:163], v[184:187], off
	v_pk_add_f32 v[20:21], v[20:21], v[176:177]
	v_pk_add_f32 v[22:23], v[22:23], v[178:179]
	v_cvt_pk_bf16_f32 v188, v20, v21
	v_cvt_pk_bf16_f32 v189, v22, v23
	v_fmac_f32_e32 v192, v20, v20
	v_fmac_f32_e32 v192, v21, v21
	v_fmac_f32_e32 v192, v22, v22
	v_fmac_f32_e32 v192, v23, v23
	v_pk_add_f32 v[16:17], v[16:17], v[180:181]
	v_pk_add_f32 v[18:19], v[18:19], v[182:183]
	v_cvt_pk_bf16_f32 v190, v16, v17
	v_cvt_pk_bf16_f32 v191, v18, v19
	v_fmac_f32_e32 v192, v16, v16
	v_fmac_f32_e32 v192, v17, v17
	v_fmac_f32_e32 v192, v18, v18
	v_fmac_f32_e32 v192, v19, v19
	global_store_dwordx4 v[162:163], v[188:191], off offset:256
	ds_bpermute_b32 v193, v194, v192
	s_waitcnt lgkmcnt(0)
	v_add_f32_e32 v192, v192, v193
	ds_bpermute_b32 v193, v195, v192
	v_lshl_add_u64 v[196:197], v[164:165], 2, s[10:11]
	s_waitcnt lgkmcnt(0)
	v_add_f32_e32 v192, v192, v193
	s_and_saveexec_b64 s[22:23], s[0:1]
	global_atomic_add_f32 v[196:197], v192, off
	s_or_b64 exec, exec, s[22:23]
	v_lshl_add_u64 v[162:163], v[162:163], 0, s[90:91]
	v_add_u32_e32 v164, 16, v164
	s_waitcnt vmcnt(2)
	v_pk_add_f32 v[12:13], v[12:13], v[200:201]
	v_pk_add_f32 v[14:15], v[14:15], v[202:203]
	v_cvt_pk_bf16_f32 v184, v12, v13
	v_cvt_pk_bf16_f32 v185, v14, v15
	v_mul_f32_e32 v192, v12, v12
	v_fmac_f32_e32 v192, v13, v13
	v_fmac_f32_e32 v192, v14, v14
	v_fmac_f32_e32 v192, v15, v15
	v_pk_add_f32 v[8:9], v[8:9], v[204:205]
	v_pk_add_f32 v[10:11], v[10:11], v[206:207]
	v_cvt_pk_bf16_f32 v186, v8, v9
	v_cvt_pk_bf16_f32 v187, v10, v11
	v_fmac_f32_e32 v192, v8, v8
	v_fmac_f32_e32 v192, v9, v9
	v_fmac_f32_e32 v192, v10, v10
	v_fmac_f32_e32 v192, v11, v11
	global_store_dwordx4 v[162:163], v[184:187], off
	v_pk_add_f32 v[4:5], v[4:5], v[208:209]
	v_pk_add_f32 v[6:7], v[6:7], v[210:211]
	v_cvt_pk_bf16_f32 v188, v4, v5
	v_cvt_pk_bf16_f32 v189, v6, v7
	v_fmac_f32_e32 v192, v4, v4
	v_fmac_f32_e32 v192, v5, v5
	v_fmac_f32_e32 v192, v6, v6
	v_fmac_f32_e32 v192, v7, v7
	v_pk_add_f32 v[0:1], v[0:1], v[212:213]
	v_pk_add_f32 v[2:3], v[2:3], v[214:215]
	v_cvt_pk_bf16_f32 v190, v0, v1
	v_cvt_pk_bf16_f32 v191, v2, v3
	v_fmac_f32_e32 v192, v0, v0
	v_fmac_f32_e32 v192, v1, v1
	v_fmac_f32_e32 v192, v2, v2
	v_fmac_f32_e32 v192, v3, v3
	global_store_dwordx4 v[162:163], v[188:191], off offset:256
	ds_bpermute_b32 v193, v194, v192
	s_waitcnt lgkmcnt(0)
	v_add_f32_e32 v192, v192, v193
	ds_bpermute_b32 v193, v195, v192
	v_lshl_add_u64 v[196:197], v[164:165], 2, s[10:11]
	s_waitcnt lgkmcnt(0)
	v_add_f32_e32 v192, v192, v193
	s_and_saveexec_b64 s[22:23], s[0:1]
	global_atomic_add_f32 v[196:197], v192, off
	s_or_b64 exec, exec, s[22:23]
	s_andn2_b64 vcc, exec, s[2:3]
	s_mov_b64 s[2:3], -1
	s_cbranch_vccnz .LBB0_1069
	s_andn2_b64 vcc, exec, s[6:7]
	s_cbranch_vccnz .LBB0_1068
	s_barrier
	s_branch .LBB0_1068
